# WO residual epilogue gets the same y_old L2 touch burst as FFO; on top of barrier trims + no setprio flips
# baseline (speedup 1.0000x reference)
.LBB0_1109:
	s_and_b64 vcc, exec, s[14:15]
	s_cbranch_vccz .LBB0_1172
	s_add_u32 s16, s12, 0x1aa00000
	s_mul_i32 s0, s36, 3
	s_mul_i32 s6, s36, 0x36000
	s_addc_u32 s17, s13, 0
	s_add_i32 s1, s0, 1
	s_add_i32 s7, s6, 0x12000
	s_mul_hi_i32 s1, s1, 0x12000
	s_add_u32 s7, s12, s7
	s_addc_u32 s1, s13, s1
	s_add_u32 s14, s7, 0x20000
	v_readlane_b32 s7, v254, 44
	s_addc_u32 s15, s1, 0
	s_mul_hi_i32 s0, s0, 0x12000
	v_mov_b32_e32 v2, s7
	ds_read_b32 v2, v2
	s_add_u32 s1, s12, s6
	v_readlane_b32 s7, v254, 45
	s_addc_u32 s6, s13, s0
	s_add_u32 s0, s1, 0x20000
	s_waitcnt lgkmcnt(0)
	v_mov_b32_e32 v4, s7
	v_readlane_b32 s7, v254, 46
	s_addc_u32 s1, s6, 0
	v_readlane_b32 s6, v254, 38
	v_mov_b32_e32 v5, s7
	v_readlane_b32 s7, v254, 47
	v_readfirstlane_b32 s28, v2
	v_mov_b32_e32 v2, s6
	s_waitcnt vmcnt(0)
	v_lshl_add_u32 v140, v191, 3, s70
	v_and_b32_e32 v141, 0x100, v0
	v_lshl_add_u32 v140, s3, 8, v140
	v_lshrrev_b32_e32 v141, 2, v141
	v_add_u32_e32 v141, v141, v189
	v_lshl_add_u32 v141, s4, 8, v141
	v_lshlrev_b32_e32 v141, 12, v141
	v_lshl_add_u32 v141, v140, 1, v141
	global_load_dword v137, v141, s[16:17]
	global_load_dword v137, v141, s[16:17] offset:256
	v_add_u32_e32 v136, 0x10000, v141
	global_load_dword v137, v136, s[16:17]
	global_load_dword v137, v136, s[16:17] offset:256
	v_add_u32_e32 v136, 0x20000, v141
	global_load_dword v137, v136, s[16:17]
	global_load_dword v137, v136, s[16:17] offset:256
	v_add_u32_e32 v136, 0x30000, v141
	global_load_dword v137, v136, s[16:17]
	global_load_dword v137, v136, s[16:17] offset:256
	v_add_u32_e32 v136, 0x80000, v141
	global_load_dword v137, v136, s[16:17]
	global_load_dword v137, v136, s[16:17] offset:256
	v_add_u32_e32 v136, 0x90000, v141
	global_load_dword v137, v136, s[16:17]
	global_load_dword v137, v136, s[16:17] offset:256
	v_add_u32_e32 v136, 0xa0000, v141
	global_load_dword v137, v136, s[16:17]
	global_load_dword v137, v136, s[16:17] offset:256
	v_add_u32_e32 v136, 0xb0000, v141
	global_load_dword v137, v136, s[16:17]
	global_load_dword v137, v136, s[16:17] offset:256
	v_mov_b32_e32 v134, s7
	ds_read_b32 v4, v4
	ds_read_b32 v5, v5
	ds_read_b32 v134, v134
	ds_read_b32 v2, v2
	v_readlane_b32 s6, v254, 39
	s_waitcnt lgkmcnt(3)
	v_readfirstlane_b32 s29, v4
	s_waitcnt lgkmcnt(2)
	v_readfirstlane_b32 s42, v5
	s_waitcnt lgkmcnt(0)
	v_mov_b32_e32 v2, s6
	ds_read_b32 v2, v2
	v_readlane_b32 s6, v254, 40
	v_readfirstlane_b32 s43, v134
	s_cmp_eq_u64 s[0:1], 0
	s_waitcnt lgkmcnt(0)
	v_mov_b32_e32 v2, s6
	ds_read_b32 v2, v2
	v_readlane_b32 s6, v254, 41
	s_waitcnt lgkmcnt(0)
	s_nop 0
	v_mov_b32_e32 v2, s6
	ds_read_b32 v2, v2
	v_readlane_b32 s6, v255, 18
	s_waitcnt lgkmcnt(0)
	v_lshl_add_u32 v2, v191, 3, s70
	v_lshl_add_u32 v178, s3, 8, v2
	v_add_u32_e32 v4, s6, v189
	v_lshl_add_u32 v180, s4, 8, v4
	v_ashrrev_i32_e32 v179, 31, v178
	v_ashrrev_i32_e32 v181, 31, v180
	s_cbranch_scc1 .LBB0_1113
	v_lshlrev_b64 v[138:139], 12, v[180:181]
	s_mov_b64 s[0:1], 0x10000
	v_lshl_add_u64 v[212:213], v[138:139], 0, s[0:1]
	s_mov_b64 s[0:1], 0x20000
	v_lshl_add_u64 v[210:211], v[138:139], 0, s[0:1]
	s_mov_b64 s[0:1], 0x30000
	v_lshl_add_u64 v[184:185], v[178:179], 1, s[16:17]
	v_lshl_add_u64 v[208:209], v[138:139], 0, s[0:1]
	v_lshl_add_u64 v[204:205], v[184:185], 0, v[212:213]
	v_lshl_add_u64 v[182:183], v[184:185], 0, v[208:209]
	v_lshl_add_u64 v[186:187], v[184:185], 0, v[210:211]
	global_load_dwordx4 v[170:173], v[204:205], off
	global_load_dwordx4 v[166:169], v[186:187], off
	global_load_dwordx4 v[158:161], v[182:183], off
	v_lshlrev_b32_e32 v4, 3, v4
	v_add_u32_e32 v216, 0, v4
	v_add_u32_e32 v4, 0x20000, v216
	ds_read2_b64 v[174:177], v4 offset1:16
	v_lshl_add_u32 v2, v2, 2, 0
	v_add_u32_e32 v197, 0x20800, v2
	v_add_u32_e32 v199, 0x20c00, v2
	ds_read2_b64 v[162:165], v4 offset0:32 offset1:48
	s_waitcnt lgkmcnt(1)
	v_mul_f32_e32 v201, 0x3a000000, v174
	v_mul_f32_e32 v5, v201, v201
	v_fma_f32 v5, v175, s72, -v5
	v_add_f32_e32 v5, 0x3727c5ac, v5
	ds_read_b128 v[150:153], v197
	ds_read_b128 v[142:145], v197 offset:16
	ds_read_b128 v[154:157], v199
	ds_read_b128 v[146:149], v199 offset:16
	v_rsq_f32_e32 v206, v5
	s_and_b32 s6, s84, 1
	s_bitcmp1_b32 s84, 0
	s_cselect_b64 s[0:1], -1, 0
	s_cmp_eq_u32 s6, 0
	v_lshl_add_u64 v[174:175], v[184:185], 0, v[138:139]
	s_cbranch_scc1 .LBB0_1114
	global_load_dwordx4 v[134:137], v[174:175], off
	v_lshl_add_u64 v[138:139], s[16:17], 0, v[138:139]
	v_lshl_add_u64 v[138:139], v[178:179], 1, v[138:139]
	s_waitcnt vmcnt(0)
	v_lshlrev_b32_e32 v2, 16, v134
	v_and_b32_e32 v134, 0xffff0000, v134
	v_lshlrev_b32_e32 v4, 16, v135
	v_and_b32_e32 v5, 0xffff0000, v135
	v_lshlrev_b32_e32 v207, 16, v137
	v_sub_f32_e32 v5, v5, v201
	v_sub_f32_e32 v4, v4, v201
	v_sub_f32_e32 v135, v134, v201
	v_sub_f32_e32 v134, v2, v201
	v_pk_mul_f32 v[134:135], v[206:207], v[134:135] op_sel_hi:[0,1]
	v_pk_mul_f32 v[4:5], v[206:207], v[4:5] op_sel_hi:[0,1]
	v_lshlrev_b32_e32 v203, 16, v136
	v_and_b32_e32 v136, 0xffff0000, v136
	v_and_b32_e32 v137, 0xffff0000, v137
	s_waitcnt lgkmcnt(1)
	v_pk_fma_f32 v[4:5], v[152:153], v[4:5], v[156:157]
	v_pk_fma_f32 v[134:135], v[150:151], v[134:135], v[154:155]
	v_pk_fma_f32 v[214:215], v[4:5], s[76:77], v[128:129] op_sel_hi:[1,0,1]
	v_pk_fma_f32 v[140:141], v[134:135], s[76:77], v[126:127] op_sel_hi:[1,0,1]
	v_sub_f32_e32 v5, v137, v201
	v_sub_f32_e32 v4, v207, v201
	v_sub_f32_e32 v135, v136, v201
	v_sub_f32_e32 v134, v203, v201
	v_pk_mul_f32 v[134:135], v[206:207], v[134:135] op_sel_hi:[0,1]
	v_pk_mul_f32 v[4:5], v[206:207], v[4:5] op_sel_hi:[0,1]
	s_waitcnt lgkmcnt(0)
	v_pk_fma_f32 v[4:5], v[144:145], v[4:5], v[148:149]
	v_pk_fma_f32 v[134:135], v[142:143], v[134:135], v[146:147]
	v_pk_fma_f32 v[222:223], v[4:5], s[76:77], v[132:133] op_sel_hi:[1,0,1]
	v_pk_fma_f32 v[218:219], v[134:135], s[76:77], v[130:131] op_sel_hi:[1,0,1]
	v_pk_add_f32 v[4:5], v[214:215], v[222:223]
	v_pk_add_f32 v[134:135], v[140:141], v[218:219]
	v_pk_mul_f32 v[136:137], v[218:219], v[218:219]
	v_pk_mul_f32 v[224:225], v[222:223], v[222:223]
	v_pk_fma_f32 v[136:137], v[140:141], v[140:141], v[136:137]
	v_pk_fma_f32 v[224:225], v[214:215], v[214:215], v[224:225]
	v_pk_mov_b32 v[226:227], v[134:135], v[4:5] op_sel:[1,0]
	v_mov_b32_e32 v135, v5
	v_pk_add_f32 v[4:5], v[226:227], v[134:135]
	v_pk_mov_b32 v[134:135], v[136:137], v[224:225] op_sel:[1,0]
	v_mov_b32_e32 v137, v225
	v_pk_add_f32 v[134:135], v[134:135], v[136:137]
	v_add_f32_e32 v2, v4, v5
	v_pk_add_f32 v[134:135], v[134:135], v[134:135] op_sel:[0,1] op_sel_hi:[1,0]
	v_add_f32_e32 v2, 0, v2
	v_mov_b32_e32 v4, v3
	v_mov_b32_e32 v5, v3
	v_mov_b32_e32 v135, v3
	v_mov_b32_e32 v136, v3
	v_mov_b32_e32 v137, v3
	v_cvt_pk_bf16_f32 v224, v140, v141
	v_cvt_pk_bf16_f32 v225, v214, v215
	v_cvt_pk_bf16_f32 v226, v218, v219
	v_cvt_pk_bf16_f32 v227, v222, v223
	global_store_dwordx4 v[138:139], v[224:227], off
	s_branch .LBB0_1115
